# combo8 + w_out and w_in first K-iteration peeled with SrcC=0 (accumulator zeroing removed for all 62 tiles)
# speedup vs baseline: 1.0088x; 1.0035x over previous
; #define PG8_STAGE(bufoff, gbase, voff) do { _Pragma("unroll") for (int _i = 0; _i < 2; ++_i) \
;         __builtin_amdgcn_global_load_lds((const unsigned*)((const char*)(gbase) + (voff)[_i]), (PG8_LAS unsigned*)(lds + (bufoff) + ldsw + _i * 8192), 16, 0, 0); } while (0)
; #define PG8_LDA(dst, b, h) do { _Pragma("unroll") for (int m = 0; m < 4; ++m) _Pragma("unroll") for (int k = 0; k < 2; ++k) dst[m][k] = *(const PG8_LAS bf16x8*)(lds + PG8_SA(b, h) + aoff + m * 2048 + k * 1024); } while (0)
; #define PG8_LDB(dst, b, h) do { _Pragma("unroll") for (int n = 0; n < 2; ++n) _Pragma("unroll") for (int k = 0; k < 2; ++k) dst[n][k] = *(const PG8_LAS bf16x8*)(lds + PG8_SB(b, h) + boff + n * 2048 + k * 1024); } while (0)
; #define PG8_WAIT_V(n) asm volatile("s_waitcnt vmcnt(" #n ")" ::: "memory")
; template <class Epi, class Sched, bool ALIGN_EPI = false, bool SP2 = false>
; __device__ __forceinline__ void gemm_phase(PG8_LAS unsigned char* lds, const Gemm g, const Sched& S, const Epi& E, const int tid) {
;     ...
;         const char* nA = has_next ? (const char*)g.A + (size_t)nxt.pm * tstep : cA; const char* nB = has_next ? (const char*)g.Bt + (size_t)nxt.pn * tstep : cB;
;         for (int t = 0; t < nt; t += 2) {
;             const bool last = (t == nt - 2);
;             const char* a1 = cA + (size_t)(t + 1) * kstep;
;             const char* a2 = last ? nA : cA + (size_t)(t + 2) * kstep; const char* b2 = last ? nB : cB + (size_t)(t + 2) * kstep;
;             const char* a3 = a2 + kstep; const char* b3 = b2 + kstep;
;             if (last && has_next) S.a_ready(nxt);
;             if (last) E.prefetch(lds + EPI_LDS_OFF + wid * 1024, cur, wr, wc, lane);
;             if constexpr (SP2) {
;             PG8_LDB(B0, 0, 0); PG8_LDB(B1, 0, 1); PG8_SCHED; PG8_LDA(At, 0, 0); PG8_STAGE(PG8_SA(1, 1), a1 + hstep, voffA);
;             PG8_WAIT_V(8); PG8_WAIT_L(0); PG8_BAR; PG8_MMA(0, 0, At, B0); PG8_MMA(0, 1, At, B1); PG8_BAR; PG8_SCHED;
;             PG8_LDA(At, 0, 1); PG8_STAGE(PG8_SB(0, 0), b2, voffB); PG8_STAGE(PG8_SB(0, 1), b2 + hstep, voffB); PG8_STAGE(PG8_SA(0, 0), a2, voffA);
;     __device__ __forceinline__ void prefetch(LAS unsigned char* sl, const pg8::Unit& u, int wr, int wc, int lane) const {
;     ...
;         const int col = u.pn * pg8::BM + wc * 32 + (lane & 31) + (lane >> 5) * pg8::HALF; const size_t bo = (size_t)(u.pm / (SEQ / 256)) * MODW;
.LBB0_73:
	s_ashr_i32 s17, s16, 31
	s_lshl_b64 s[18:19], s[16:17], 20
	s_add_u32 s18, s5, s18
	s_addc_u32 s19, s37, s19
	s_and_b64 s[20:21], s[8:9], exec
	s_cselect_b32 s17, s19, s29
	s_cselect_b32 s23, s18, s28
	s_ashr_i32 s15, s14, 31
	s_lshl_b64 s[20:21], s[14:15], 20
	s_add_u32 s20, s39, s20
	s_addc_u32 s21, s44, s21
	s_and_b64 s[30:31], s[8:9], exec
	s_cselect_b32 s99, s21, s27
	s_cselect_b32 vcc_lo, s20, s26
	s_lshl_b32 s15, s24, 8
	s_ashr_i32 s24, s22, 31
	s_lshr_b32 s24, s24, 27
	s_add_i32 s24, s22, s24
	s_ashr_i32 s24, s24, 5
	s_mul_hi_i32 s31, s24, 0x4800
	s_mul_i32 s30, s24, 0x4800
	s_add_u32 s24, s28, 0x80080
	v_or_b32_e32 v6, s15, v249
	s_addc_u32 s25, s29, 0
	v_ashrrev_i32_e32 v7, 31, v6
	s_add_u32 vcc_hi, s26, 0x100
	s_addc_u32 s50, s27, 0
	s_mov_b32 s51, -2
	s_lshl_b64 s[26:27], s[30:31], 2
	v_lshlrev_b64 v[96:97], 2, v[6:7]
	s_waitcnt vmcnt(0)
	s_mov_b64 s[28:29], 0
.Lwo_peel:
	s_add_u32 s30, s24, 0xfff80080
	s_addc_u32 s31, s25, -1
	s_and_b64 s[28:29], s[28:29], exec
	s_cselect_b32 s31, s17, s31
	s_cselect_b32 s30, s23, s30
	s_cselect_b32 s29, s99, s50
	s_cselect_b32 s28, vcc_lo, vcc_hi
	s_add_i32 s42, 0, 0x10000
	v_add_u32_e32 v110, s42, v247
	s_add_i32 s3, 0, 0x14000
	ds_read_b128 v[98:101], v110
	ds_read_b128 v[102:105], v110 offset:1024
	ds_read_b128 v[106:109], v110 offset:2048
	ds_read_b128 v[144:147], v110 offset:3072
	v_add_u32_e32 v110, s3, v247
	ds_read_b128 v[152:155], v110
	ds_read_b128 v[156:159], v110 offset:1024
	ds_read_b128 v[160:163], v110 offset:2048
	ds_read_b128 v[164:167], v110 offset:3072
	v_lshl_add_u64 v[110:111], s[24:25], 0, v[190:191]
	s_add_i32 m0, s49, 0xc000
	ds_read_b128 v[168:171], v253
	ds_read_b128 v[172:175], v253 offset:1024
	ds_read_b128 v[176:179], v253 offset:2048
	ds_read_b128 v[194:197], v253 offset:3072
	ds_read_b128 v[198:201], v253 offset:4096
	ds_read_b128 v[202:205], v253 offset:5120
	ds_read_b128 v[206:209], v253 offset:6144
	ds_read_b128 v[210:213], v253 offset:7168
	global_load_lds_dwordx4 v[110:111], off
	v_lshl_add_u64 v[110:111], s[24:25], 0, v[192:193]
	s_add_i32 m0, s49, 0xe000
	s_nop 0
	global_load_lds_dwordx4 v[110:111], off
	s_waitcnt vmcnt(8)
	s_waitcnt lgkmcnt(0)
	s_setprio 1
	s_barrier
	v_mfma_f32_16x16x32_bf16 v[148:151], v[98:101], v[168:171], 0
	v_mfma_f32_16x16x32_bf16 v[140:143], v[106:109], v[168:171], 0
	v_mfma_f32_16x16x32_bf16 v[128:131], v[98:101], v[176:179], 0
	v_mfma_f32_16x16x32_bf16 v[124:127], v[106:109], v[176:179], 0
	v_mfma_f32_16x16x32_bf16 v[110:113], v[98:101], v[198:201], 0
	v_mfma_f32_16x16x32_bf16 v[92:95], v[106:109], v[198:201], 0
	v_mfma_f32_16x16x32_bf16 v[80:83], v[98:101], v[206:209], 0
	v_mfma_f32_16x16x32_bf16 v[76:79], v[106:109], v[206:209], 0
	v_mfma_f32_16x16x32_bf16 v[148:151], v[102:105], v[172:175], v[148:151]
	v_mfma_f32_16x16x32_bf16 v[140:143], v[144:147], v[172:175], v[140:143]
	v_mfma_f32_16x16x32_bf16 v[128:131], v[102:105], v[194:197], v[128:131]
	v_mfma_f32_16x16x32_bf16 v[124:127], v[144:147], v[194:197], v[124:127]
	v_mfma_f32_16x16x32_bf16 v[110:113], v[102:105], v[202:205], v[110:113]
	v_mfma_f32_16x16x32_bf16 v[92:95], v[144:147], v[202:205], v[92:95]
	v_mfma_f32_16x16x32_bf16 v[80:83], v[102:105], v[210:213], v[80:83]
	v_mfma_f32_16x16x32_bf16 v[76:79], v[144:147], v[210:213], v[76:79]
	s_setprio 0
	s_setprio 1
	v_mfma_f32_16x16x32_bf16 v[136:139], v[152:155], v[168:171], 0
	v_mfma_f32_16x16x32_bf16 v[132:135], v[160:163], v[168:171], 0
	v_mfma_f32_16x16x32_bf16 v[120:123], v[152:155], v[176:179], 0
	v_mfma_f32_16x16x32_bf16 v[114:117], v[160:163], v[176:179], 0
	v_mfma_f32_16x16x32_bf16 v[88:91], v[152:155], v[198:201], 0
	v_mfma_f32_16x16x32_bf16 v[84:87], v[160:163], v[198:201], 0
	v_mfma_f32_16x16x32_bf16 v[72:75], v[152:155], v[206:209], 0
	v_mfma_f32_16x16x32_bf16 v[68:71], v[160:163], v[206:209], 0
	v_mfma_f32_16x16x32_bf16 v[136:139], v[156:159], v[172:175], v[136:139]
	v_mfma_f32_16x16x32_bf16 v[132:135], v[164:167], v[172:175], v[132:135]
	v_mfma_f32_16x16x32_bf16 v[120:123], v[156:159], v[194:197], v[120:123]
	v_mfma_f32_16x16x32_bf16 v[116:119], v[164:167], v[194:197], v[114:117]
	v_mfma_f32_16x16x32_bf16 v[88:91], v[156:159], v[202:205], v[88:91]
	v_mfma_f32_16x16x32_bf16 v[84:87], v[164:167], v[202:205], v[84:87]
	v_mfma_f32_16x16x32_bf16 v[72:75], v[156:159], v[210:213], v[72:75]
	v_mfma_f32_16x16x32_bf16 v[68:71], v[164:167], v[210:213], v[68:71]
	s_setprio 0
	s_barrier
	s_add_i32 s42, s42, s48
	v_lshl_add_u64 v[180:181], s[28:29], 0, v[2:3]
	s_mov_b32 m0, s42
	ds_read_b128 v[168:171], v253 offset:16384
	ds_read_b128 v[172:175], v253 offset:17408
	ds_read_b128 v[176:179], v253 offset:18432
	ds_read_b128 v[194:197], v253 offset:19456
	ds_read_b128 v[198:201], v253 offset:20480
	ds_read_b128 v[202:205], v253 offset:21504
	ds_read_b128 v[206:209], v253 offset:22528
	ds_read_b128 v[210:213], v253 offset:23552
	global_load_lds_dwordx4 v[180:181], off
	s_add_i32 m0, s42, 0x2000
	s_add_u32 s42, s28, 0x80000
	v_lshl_add_u64 v[182:183], s[28:29], 0, v[188:189]
	s_addc_u32 s43, s29, 0
	s_add_i32 s3, s3, s48
	global_load_lds_dwordx4 v[182:183], off
	v_lshl_add_u64 v[114:115], s[42:43], 0, v[2:3]
	s_mov_b32 m0, s3
	v_lshl_add_u64 v[214:215], s[30:31], 0, v[0:1]
	global_load_lds_dwordx4 v[114:115], off
	v_lshl_add_u64 v[114:115], s[42:43], 0, v[188:189]
	s_add_i32 m0, s3, 0x2000
	v_lshl_add_u64 v[216:217], s[30:31], 0, v[186:187]
	global_load_lds_dwordx4 v[114:115], off
	s_mov_b32 m0, s49
	s_nop 0
	global_load_lds_dwordx4 v[214:215], off
	s_mov_b32 m0, s52
	s_nop 0
	global_load_lds_dwordx4 v[216:217], off
	s_waitcnt vmcnt(8)
	s_waitcnt lgkmcnt(0)
	s_setprio 1
	s_barrier
; #define PG8_STAGE(bufoff, gbase, voff) do { _Pragma("unroll") for (int _i = 0; _i < 2; ++_i) \
;         __builtin_amdgcn_global_load_lds((const unsigned*)((const char*)(gbase) + (voff)[_i]), (PG8_LAS unsigned*)(lds + (bufoff) + ldsw + _i * 8192), 16, 0, 0); } while (0)
; #define PG8_LDA(dst, b, h) do { _Pragma("unroll") for (int m = 0; m < 4; ++m) _Pragma("unroll") for (int k = 0; k < 2; ++k) dst[m][k] = *(const PG8_LAS bf16x8*)(lds + PG8_SA(b, h) + aoff + m * 2048 + k * 1024); } while (0)
; #define PG8_LDB(dst, b, h) do { _Pragma("unroll") for (int n = 0; n < 2; ++n) _Pragma("unroll") for (int k = 0; k < 2; ++k) dst[n][k] = *(const PG8_LAS bf16x8*)(lds + PG8_SB(b, h) + boff + n * 2048 + k * 1024); } while (0)
; #define PG8_MMA(ai, bj, At, Bt) do { __builtin_amdgcn_s_setprio(1); _Pragma("unroll") for (int m = 0; m < 4; ++m) _Pragma("unroll") for (int n = 0; n < 2; ++n) _Pragma("unroll") for (int k = 0; k < 2; ++k) \
;         acc[ai][bj][m][n] = __builtin_amdgcn_mfma_f32_16x16x32_bf16(Bt[n][k], At[m][k], acc[ai][bj][m][n], 0, 0, 0); __builtin_amdgcn_s_setprio(0); } while (0)
; #define PG8_WAIT_V(n) asm volatile("s_waitcnt vmcnt(" #n ")" ::: "memory")
; #define PG8_WAIT_L(n) asm volatile("s_waitcnt lgkmcnt(" #n ")" ::: "memory")
; #define PG8_BAR __builtin_amdgcn_s_barrier()
; #define PG8_SCHED __builtin_amdgcn_sched_barrier(0)
; template <class Epi, class Sched, bool ALIGN_EPI = false, bool SP2 = false>
; __device__ __forceinline__ void gemm_phase(PG8_LAS unsigned char* lds, const Gemm g, const Sched& S, const Epi& E, const int tid) {
;     ...
;             PG8_WAIT_V(8); PG8_WAIT_L(0); PG8_BAR; PG8_MMA(1, 0, At, B0); PG8_MMA(1, 1, At, B1); PG8_BAR; PG8_SCHED;
;             PG8_LDB(B0, 1, 0); PG8_LDB(B1, 1, 1); PG8_SCHED; PG8_LDA(At, 1, 0); PG8_STAGE(PG8_SA(0, 1), a2 + hstep, voffA);
;             PG8_WAIT_V(8); PG8_WAIT_L(0); PG8_BAR; PG8_MMA(0, 0, At, B0); PG8_MMA(0, 1, At, B1); PG8_BAR; PG8_SCHED;
	v_mfma_f32_16x16x32_bf16 v[64:67], v[98:101], v[168:171], 0
	v_mfma_f32_16x16x32_bf16 v[60:63], v[106:109], v[168:171], 0
	v_mfma_f32_16x16x32_bf16 v[48:51], v[98:101], v[176:179], 0
	v_mfma_f32_16x16x32_bf16 v[44:47], v[106:109], v[176:179], 0
	v_mfma_f32_16x16x32_bf16 v[32:35], v[98:101], v[198:201], 0
	v_mfma_f32_16x16x32_bf16 v[28:31], v[106:109], v[198:201], 0
	v_mfma_f32_16x16x32_bf16 v[16:19], v[98:101], v[206:209], 0
	v_mfma_f32_16x16x32_bf16 v[12:15], v[106:109], v[206:209], 0
	v_mfma_f32_16x16x32_bf16 v[64:67], v[102:105], v[172:175], v[64:67]
	v_mfma_f32_16x16x32_bf16 v[60:63], v[144:147], v[172:175], v[60:63]
	v_mfma_f32_16x16x32_bf16 v[48:51], v[102:105], v[194:197], v[48:51]
	v_mfma_f32_16x16x32_bf16 v[44:47], v[144:147], v[194:197], v[44:47]
	v_mfma_f32_16x16x32_bf16 v[32:35], v[102:105], v[202:205], v[32:35]
	v_mfma_f32_16x16x32_bf16 v[28:31], v[144:147], v[202:205], v[28:31]
	v_mfma_f32_16x16x32_bf16 v[16:19], v[102:105], v[210:213], v[16:19]
	v_mfma_f32_16x16x32_bf16 v[12:15], v[144:147], v[210:213], v[12:15]
	s_setprio 0
	s_setprio 1
	v_mfma_f32_16x16x32_bf16 v[56:59], v[152:155], v[168:171], 0
	v_mfma_f32_16x16x32_bf16 v[52:55], v[160:163], v[168:171], 0
	v_mfma_f32_16x16x32_bf16 v[40:43], v[152:155], v[176:179], 0
	v_mfma_f32_16x16x32_bf16 v[36:39], v[160:163], v[176:179], 0
	v_mfma_f32_16x16x32_bf16 v[24:27], v[152:155], v[198:201], 0
	v_mfma_f32_16x16x32_bf16 v[20:23], v[160:163], v[198:201], 0
	v_mfma_f32_16x16x32_bf16 v[8:11], v[152:155], v[206:209], 0
	v_mfma_f32_16x16x32_bf16 v[4:7], v[160:163], v[206:209], 0
	v_mfma_f32_16x16x32_bf16 v[56:59], v[156:159], v[172:175], v[56:59]
	v_mfma_f32_16x16x32_bf16 v[52:55], v[164:167], v[172:175], v[52:55]
	v_mfma_f32_16x16x32_bf16 v[40:43], v[156:159], v[194:197], v[40:43]
	v_mfma_f32_16x16x32_bf16 v[36:39], v[164:167], v[194:197], v[36:39]
	v_mfma_f32_16x16x32_bf16 v[24:27], v[156:159], v[202:205], v[24:27]
	v_mfma_f32_16x16x32_bf16 v[20:23], v[164:167], v[202:205], v[20:23]
	v_mfma_f32_16x16x32_bf16 v[8:11], v[156:159], v[210:213], v[8:11]
	v_mfma_f32_16x16x32_bf16 v[4:7], v[164:167], v[210:213], v[4:7]
	s_setprio 0
	s_barrier
	s_add_i32 s3, 0, 0x18000
	v_add_u32_e32 v114, s3, v247
	s_add_i32 s42, 0, 0x1c000
	ds_read_b128 v[98:101], v114
	ds_read_b128 v[102:105], v114 offset:1024
	ds_read_b128 v[106:109], v114 offset:2048
	ds_read_b128 v[144:147], v114 offset:3072
	v_add_u32_e32 v114, s42, v247
	ds_read_b128 v[152:155], v114
	ds_read_b128 v[156:159], v114 offset:1024
	ds_read_b128 v[160:163], v114 offset:2048
	ds_read_b128 v[164:167], v114 offset:3072
	s_add_u32 s30, s30, 0x80000
	s_addc_u32 s31, s31, 0
	s_mov_b32 m0, s53
	v_lshl_add_u64 v[114:115], s[30:31], 0, v[0:1]
	ds_read_b128 v[168:171], v253 offset:32768
	ds_read_b128 v[172:175], v253 offset:33792
	ds_read_b128 v[176:179], v253 offset:34816
	ds_read_b128 v[194:197], v253 offset:35840
	ds_read_b128 v[198:201], v253 offset:36864
	ds_read_b128 v[202:205], v253 offset:37888
	ds_read_b128 v[206:209], v253 offset:38912
	ds_read_b128 v[210:213], v253 offset:39936
	global_load_lds_dwordx4 v[114:115], off
	v_lshl_add_u64 v[114:115], s[30:31], 0, v[186:187]
	s_mov_b32 m0, s54
	s_nop 0
	global_load_lds_dwordx4 v[114:115], off
	s_waitcnt vmcnt(8)
	s_waitcnt lgkmcnt(0)
	s_setprio 1
	s_barrier
	v_mfma_f32_16x16x32_bf16 v[148:151], v[98:101], v[168:171], v[148:151]
	v_mfma_f32_16x16x32_bf16 v[140:143], v[106:109], v[168:171], v[140:143]
	v_mfma_f32_16x16x32_bf16 v[128:131], v[98:101], v[176:179], v[128:131]
	v_mfma_f32_16x16x32_bf16 v[124:127], v[106:109], v[176:179], v[124:127]
	v_mfma_f32_16x16x32_bf16 v[110:113], v[98:101], v[198:201], v[110:113]
	v_mfma_f32_16x16x32_bf16 v[92:95], v[106:109], v[198:201], v[92:95]
	v_mfma_f32_16x16x32_bf16 v[80:83], v[98:101], v[206:209], v[80:83]
	v_mfma_f32_16x16x32_bf16 v[76:79], v[106:109], v[206:209], v[76:79]
	v_mfma_f32_16x16x32_bf16 v[148:151], v[102:105], v[172:175], v[148:151]
	v_mfma_f32_16x16x32_bf16 v[140:143], v[144:147], v[172:175], v[140:143]
	v_mfma_f32_16x16x32_bf16 v[128:131], v[102:105], v[194:197], v[128:131]
	v_mfma_f32_16x16x32_bf16 v[124:127], v[144:147], v[194:197], v[124:127]
	v_mfma_f32_16x16x32_bf16 v[112:115], v[102:105], v[202:205], v[110:113]
	v_mfma_f32_16x16x32_bf16 v[92:95], v[144:147], v[202:205], v[92:95]
	v_mfma_f32_16x16x32_bf16 v[80:83], v[102:105], v[210:213], v[80:83]
	v_mfma_f32_16x16x32_bf16 v[76:79], v[144:147], v[210:213], v[76:79]
	s_setprio 0
	s_setprio 1
	v_mfma_f32_16x16x32_bf16 v[136:139], v[152:155], v[168:171], v[136:139]
	v_mfma_f32_16x16x32_bf16 v[132:135], v[160:163], v[168:171], v[132:135]
	v_mfma_f32_16x16x32_bf16 v[120:123], v[152:155], v[176:179], v[120:123]
	v_mfma_f32_16x16x32_bf16 v[116:119], v[160:163], v[176:179], v[116:119]
	v_mfma_f32_16x16x32_bf16 v[88:91], v[152:155], v[198:201], v[88:91]
	v_mfma_f32_16x16x32_bf16 v[84:87], v[160:163], v[198:201], v[84:87]
	v_mfma_f32_16x16x32_bf16 v[72:75], v[152:155], v[206:209], v[72:75]
	v_mfma_f32_16x16x32_bf16 v[68:71], v[160:163], v[206:209], v[68:71]
	v_mfma_f32_16x16x32_bf16 v[136:139], v[156:159], v[172:175], v[136:139]
	v_mfma_f32_16x16x32_bf16 v[132:135], v[164:167], v[172:175], v[132:135]
	v_mfma_f32_16x16x32_bf16 v[120:123], v[156:159], v[194:197], v[120:123]
	v_mfma_f32_16x16x32_bf16 v[116:119], v[164:167], v[194:197], v[116:119]
	v_mfma_f32_16x16x32_bf16 v[88:91], v[156:159], v[202:205], v[88:91]
	v_mfma_f32_16x16x32_bf16 v[84:87], v[164:167], v[202:205], v[84:87]
	v_mfma_f32_16x16x32_bf16 v[72:75], v[156:159], v[210:213], v[72:75]
	v_mfma_f32_16x16x32_bf16 v[68:71], v[164:167], v[210:213], v[68:71]
	s_setprio 0
	s_barrier
; #define PG8_STAGE(bufoff, gbase, voff) do { _Pragma("unroll") for (int _i = 0; _i < 2; ++_i) \
;         __builtin_amdgcn_global_load_lds((const unsigned*)((const char*)(gbase) + (voff)[_i]), (PG8_LAS unsigned*)(lds + (bufoff) + ldsw + _i * 8192), 16, 0, 0); } while (0)
; #define PG8_LDA(dst, b, h) do { _Pragma("unroll") for (int m = 0; m < 4; ++m) _Pragma("unroll") for (int k = 0; k < 2; ++k) dst[m][k] = *(const PG8_LAS bf16x8*)(lds + PG8_SA(b, h) + aoff + m * 2048 + k * 1024); } while (0)
; #define PG8_MMA(ai, bj, At, Bt) do { __builtin_amdgcn_s_setprio(1); _Pragma("unroll") for (int m = 0; m < 4; ++m) _Pragma("unroll") for (int n = 0; n < 2; ++n) _Pragma("unroll") for (int k = 0; k < 2; ++k) \
;         acc[ai][bj][m][n] = __builtin_amdgcn_mfma_f32_16x16x32_bf16(Bt[n][k], At[m][k], acc[ai][bj][m][n], 0, 0, 0); __builtin_amdgcn_s_setprio(0); } while (0)
; #define PG8_WAIT_V(n) asm volatile("s_waitcnt vmcnt(" #n ")" ::: "memory")
; #define PG8_WAIT_L(n) asm volatile("s_waitcnt lgkmcnt(" #n ")" ::: "memory")
; #define PG8_BAR __builtin_amdgcn_s_barrier()
; #define PG8_SCHED __builtin_amdgcn_sched_barrier(0)
; template <class Epi, class Sched, bool ALIGN_EPI = false, bool SP2 = false>
; __device__ __forceinline__ void gemm_phase(PG8_LAS unsigned char* lds, const Gemm g, const Sched& S, const Epi& E, const int tid) {
;     ...
;         for (int t = 0; t < nt; t += 2) {
;     ...
;             PG8_LDA(At, 1, 1); PG8_STAGE(PG8_SB(1, 0), b3, voffB); PG8_STAGE(PG8_SB(1, 1), b3 + hstep, voffB); PG8_STAGE(PG8_SA(1, 0), a3, voffA);
;             PG8_WAIT_V(8); PG8_WAIT_L(0); PG8_BAR; PG8_MMA(1, 0, At, B0); PG8_MMA(1, 1, At, B1); PG8_BAR; PG8_SCHED;
	s_add_i32 s3, s3, s48
	v_lshl_add_u64 v[110:111], v[180:181], 0, s[46:47]
	s_mov_b32 m0, s3
	ds_read_b128 v[168:171], v253 offset:49152
	ds_read_b128 v[172:175], v253 offset:50176
	ds_read_b128 v[176:179], v253 offset:51200
	ds_read_b128 v[194:197], v253 offset:52224
	ds_read_b128 v[198:201], v253 offset:53248
	ds_read_b128 v[202:205], v253 offset:54272
	ds_read_b128 v[206:209], v253 offset:55296
	ds_read_b128 v[210:213], v253 offset:56320
	global_load_lds_dwordx4 v[110:111], off
	s_add_i32 m0, s3, 0x2000
	s_add_u32 s28, s28, 0x80080
	v_lshl_add_u64 v[110:111], v[182:183], 0, s[46:47]
	s_addc_u32 s29, s29, 0
	s_add_i32 s3, s42, s48
	global_load_lds_dwordx4 v[110:111], off
	v_lshl_add_u64 v[110:111], s[28:29], 0, v[2:3]
	s_mov_b32 m0, s3
	s_nop 0
	global_load_lds_dwordx4 v[110:111], off
	v_lshl_add_u64 v[110:111], s[28:29], 0, v[188:189]
	s_add_i32 m0, s3, 0x2000
	s_nop 0
	global_load_lds_dwordx4 v[110:111], off
	v_lshl_add_u64 v[110:111], v[214:215], 0, s[46:47]
	s_mov_b32 m0, s55
	s_nop 0
	global_load_lds_dwordx4 v[110:111], off
	v_lshl_add_u64 v[110:111], v[216:217], 0, s[46:47]
	s_mov_b32 m0, s74
	s_nop 0
	global_load_lds_dwordx4 v[110:111], off
	s_waitcnt vmcnt(8)
	s_waitcnt lgkmcnt(0)
	s_setprio 1
	s_barrier
	v_mfma_f32_16x16x32_bf16 v[64:67], v[98:101], v[168:171], v[64:67]
	v_mfma_f32_16x16x32_bf16 v[60:63], v[106:109], v[168:171], v[60:63]
	v_mfma_f32_16x16x32_bf16 v[48:51], v[98:101], v[176:179], v[48:51]
	v_mfma_f32_16x16x32_bf16 v[44:47], v[106:109], v[176:179], v[44:47]
	v_mfma_f32_16x16x32_bf16 v[32:35], v[98:101], v[198:201], v[32:35]
	v_mfma_f32_16x16x32_bf16 v[28:31], v[106:109], v[198:201], v[28:31]
	v_mfma_f32_16x16x32_bf16 v[16:19], v[98:101], v[206:209], v[16:19]
	v_mfma_f32_16x16x32_bf16 v[12:15], v[106:109], v[206:209], v[12:15]
	v_mfma_f32_16x16x32_bf16 v[64:67], v[102:105], v[172:175], v[64:67]
	v_mfma_f32_16x16x32_bf16 v[60:63], v[144:147], v[172:175], v[60:63]
	v_mfma_f32_16x16x32_bf16 v[48:51], v[102:105], v[194:197], v[48:51]
	v_mfma_f32_16x16x32_bf16 v[44:47], v[144:147], v[194:197], v[44:47]
	v_mfma_f32_16x16x32_bf16 v[32:35], v[102:105], v[202:205], v[32:35]
	v_mfma_f32_16x16x32_bf16 v[28:31], v[144:147], v[202:205], v[28:31]
	v_mfma_f32_16x16x32_bf16 v[16:19], v[102:105], v[210:213], v[16:19]
	v_mfma_f32_16x16x32_bf16 v[12:15], v[144:147], v[210:213], v[12:15]
	s_setprio 0
	s_setprio 1
	v_mfma_f32_16x16x32_bf16 v[56:59], v[152:155], v[168:171], v[56:59]
	v_mfma_f32_16x16x32_bf16 v[52:55], v[160:163], v[168:171], v[52:55]
	v_mfma_f32_16x16x32_bf16 v[40:43], v[152:155], v[176:179], v[40:43]
	v_mfma_f32_16x16x32_bf16 v[36:39], v[160:163], v[176:179], v[36:39]
	v_mfma_f32_16x16x32_bf16 v[24:27], v[152:155], v[198:201], v[24:27]
	v_mfma_f32_16x16x32_bf16 v[20:23], v[160:163], v[198:201], v[20:23]
	v_mfma_f32_16x16x32_bf16 v[8:11], v[152:155], v[206:209], v[8:11]
	v_mfma_f32_16x16x32_bf16 v[4:7], v[160:163], v[206:209], v[4:7]
	v_mfma_f32_16x16x32_bf16 v[56:59], v[156:159], v[172:175], v[56:59]
	v_mfma_f32_16x16x32_bf16 v[52:55], v[164:167], v[172:175], v[52:55]
	v_mfma_f32_16x16x32_bf16 v[40:43], v[156:159], v[194:197], v[40:43]
	v_mfma_f32_16x16x32_bf16 v[36:39], v[164:167], v[194:197], v[36:39]
	v_mfma_f32_16x16x32_bf16 v[24:27], v[156:159], v[202:205], v[24:27]
	v_mfma_f32_16x16x32_bf16 v[20:23], v[164:167], v[202:205], v[20:23]
	v_mfma_f32_16x16x32_bf16 v[8:11], v[156:159], v[210:213], v[8:11]
	v_mfma_f32_16x16x32_bf16 v[4:7], v[164:167], v[210:213], v[4:7]
	s_setprio 0
	s_barrier
	s_add_i32 s51, s51, 2
	s_add_u32 s24, s24, 0x100
	s_addc_u32 s25, s25, 0
	s_add_u32 vcc_hi, vcc_hi, 0x100
	s_addc_u32 s50, s50, 0
	s_cmp_gt_u32 s51, 29
	s_cbranch_scc1 .LBB0_77
	s_branch .LBB0_75

; #define PG8_LAS __attribute__((address_space(3)))
; #define PG8_LDA(dst, b, h) do { _Pragma("unroll") for (int m = 0; m < 4; ++m) _Pragma("unroll") for (int k = 0; k < 2; ++k) dst[m][k] = *(const PG8_LAS bf16x8*)(lds + PG8_SA(b, h) + aoff + m * 2048 + k * 1024); } while (0)
;     __device__ __forceinline__ void prefetch(PG8_LAS unsigned char* sl, const Unit& u, int wr, int wc, int lane) const {
;         const float* sp = ssq + u.pm * BM + wr * 64 + lane;
;         __builtin_amdgcn_global_load_lds((const unsigned*)sp, (PG8_LAS unsigned*)sl, 4, 0, 0);
;         __builtin_amdgcn_global_load_lds((const unsigned*)(sp + HALF), (PG8_LAS unsigned*)(sl + 256), 4, 0, 0);
;         const float* bp = bias2 + (size_t)(u.pm / tiles_per_batch) * bias_stride + u.pn * BM + wc * 32 + (lane & 31) + (lane >> 5) * HALF;
;         __builtin_amdgcn_global_load_lds((const unsigned*)bp, (PG8_LAS unsigned*)(sl + 512), 4, 0, 0);
; template <class Epi, class Sched, bool ALIGN_EPI = false, bool SP2 = false>
; __device__ __forceinline__ void gemm_phase(PG8_LAS unsigned char* lds, const Gemm g, const Sched& S, const Epi& E, const int tid) {
;     ...
;         const bool has_next = S.next(ui + 1, nxt);
;         const char* nA = has_next ? (const char*)g.A + (size_t)nxt.pm * tstep : cA; const char* nB = has_next ? (const char*)g.Bt + (size_t)nxt.pn * tstep : cB;
;         for (int t = 0; t < nt; t += 2) {
;             const bool last = (t == nt - 2);
;             const char* a1 = cA + (size_t)(t + 1) * kstep;
;             const char* a2 = last ? nA : cA + (size_t)(t + 2) * kstep; const char* b2 = last ? nB : cB + (size_t)(t + 2) * kstep;
;             const char* a3 = a2 + kstep; const char* b3 = b2 + kstep;
;             if (last && has_next) S.a_ready(nxt);
;             if (last) E.prefetch(lds + EPI_LDS_OFF + wid * 1024, cur, wr, wc, lane);
;             if constexpr (SP2) {
;             PG8_LDB(B0, 0, 0); PG8_LDB(B1, 0, 1); PG8_SCHED; PG8_LDA(At, 0, 0); PG8_STAGE(PG8_SA(1, 1), a1 + hstep, voffA);
;             PG8_WAIT_V(8); PG8_WAIT_L(0); PG8_BAR; PG8_MMA(0, 0, At, B0); PG8_MMA(0, 1, At, B1); PG8_BAR; PG8_SCHED;
;             PG8_LDA(At, 0, 1); PG8_STAGE(PG8_SB(0, 0), b2, voffB); PG8_STAGE(PG8_SB(0, 1), b2 + hstep, voffB); PG8_STAGE(PG8_SA(0, 0), a2, voffA);
;             PG8_WAIT_V(8); PG8_WAIT_L(0); PG8_BAR; PG8_MMA(1, 0, At, B0); PG8_MMA(1, 1, At, B1); PG8_BAR; PG8_SCHED;
.LBB0_155:
	s_ashr_i32 s17, s16, 31
	s_lshl_b64 s[18:19], s[16:17], 20
	s_add_u32 s18, s90, s18
	s_addc_u32 s19, s91, s19
	s_and_b64 s[20:21], s[6:7], exec
	s_cselect_b32 s9, s19, s31
	s_cselect_b32 s17, s18, s30
	s_ashr_i32 s15, s14, 31
	s_lshl_b64 s[20:21], s[14:15], 20
	s_add_u32 s20, s36, s20
	s_addc_u32 s21, s37, s21
	s_and_b64 s[22:23], s[6:7], exec
	s_cselect_b32 s15, s21, s29
	s_cselect_b32 s39, s20, s28
	s_ashr_i32 s3, s26, 31
	s_lshl_b32 s24, s8, 8
	s_lshr_b32 s3, s3, 27
	s_ashr_i32 s25, s24, 31
	s_add_i32 s3, s26, s3
	s_lshl_b32 s22, s26, 8
	v_lshl_add_u64 v[4:5], s[24:25], 2, v[152:153]
	s_ashr_i32 s3, s3, 5
	v_mov_b32_e32 v6, 0x3400
	s_ashr_i32 s23, s22, 31
	v_mad_i64_i32 v[32:33], s[26:27], s3, v6, v[4:5]
	s_add_u32 s26, s30, 0x80080
	s_addc_u32 s27, s31, 0
	v_lshl_add_u64 v[28:29], s[22:23], 2, v[154:155]
	s_add_u32 s23, s28, 0x100
	v_lshl_add_u64 v[30:31], v[28:29], 0, s[56:57]
	s_addc_u32 s25, s29, 0
	s_mov_b32 s50, -2
	s_mov_b64 s[28:29], 0
.Lwi_peel:
	s_add_u32 s3, s26, 0xfff80080
	s_addc_u32 s30, s27, -1
	s_and_b64 s[28:29], s[28:29], exec
	s_cselect_b32 s31, s9, s30
	s_cselect_b32 s30, s17, s3
	s_cselect_b32 s29, s15, s25
	s_cselect_b32 s28, s39, s23
	s_add_i32 s3, 0, 0x10000
	v_add_u32_e32 v34, s3, v167
	s_add_i32 s51, 0, 0x14000
	ds_read_b128 v[44:47], v34
	ds_read_b128 v[48:51], v34 offset:1024
	ds_read_b128 v[160:163], v34 offset:2048
	ds_read_b128 v[172:175], v34 offset:3072
	v_add_u32_e32 v34, s51, v167
	ds_read_b128 v[176:179], v34
	ds_read_b128 v[180:183], v34 offset:1024
	ds_read_b128 v[186:189], v34 offset:2048
	ds_read_b128 v[190:193], v34 offset:3072
	v_lshl_add_u64 v[34:35], s[26:27], 0, v[156:157]
	s_add_i32 m0, s48, 0xc000
	ds_read_b128 v[194:197], v171
	ds_read_b128 v[198:201], v171 offset:1024
	ds_read_b128 v[202:205], v171 offset:2048
	ds_read_b128 v[206:209], v171 offset:3072
	ds_read_b128 v[210:213], v171 offset:4096
	ds_read_b128 v[214:217], v171 offset:5120
	ds_read_b128 v[218:221], v171 offset:6144
	ds_read_b128 v[222:225], v171 offset:7168
	global_load_lds_dwordx4 v[34:35], off
	v_lshl_add_u64 v[34:35], s[26:27], 0, v[158:159]
	s_add_i32 m0, s48, 0xe000
	s_nop 0
	global_load_lds_dwordx4 v[34:35], off
	s_waitcnt vmcnt(8)
	s_waitcnt lgkmcnt(0)
	s_setprio 1
	s_barrier
	v_mfma_f32_16x16x32_bf16 v[144:147], v[44:47], v[194:197], 0
	v_mfma_f32_16x16x32_bf16 v[140:143], v[160:163], v[194:197], 0
	v_mfma_f32_16x16x32_bf16 v[128:131], v[44:47], v[202:205], 0
	v_mfma_f32_16x16x32_bf16 v[124:127], v[160:163], v[202:205], 0
	v_mfma_f32_16x16x32_bf16 v[112:115], v[44:47], v[210:213], 0
	v_mfma_f32_16x16x32_bf16 v[108:111], v[160:163], v[210:213], 0
	v_mfma_f32_16x16x32_bf16 v[96:99], v[44:47], v[218:221], 0
	v_mfma_f32_16x16x32_bf16 v[92:95], v[160:163], v[218:221], 0
	v_mfma_f32_16x16x32_bf16 v[144:147], v[48:51], v[198:201], v[144:147]
	v_mfma_f32_16x16x32_bf16 v[140:143], v[172:175], v[198:201], v[140:143]
	v_mfma_f32_16x16x32_bf16 v[128:131], v[48:51], v[206:209], v[128:131]
	v_mfma_f32_16x16x32_bf16 v[124:127], v[172:175], v[206:209], v[124:127]
	v_mfma_f32_16x16x32_bf16 v[112:115], v[48:51], v[214:217], v[112:115]
	v_mfma_f32_16x16x32_bf16 v[108:111], v[172:175], v[214:217], v[108:111]
	v_mfma_f32_16x16x32_bf16 v[96:99], v[48:51], v[222:225], v[96:99]
	v_mfma_f32_16x16x32_bf16 v[92:95], v[172:175], v[222:225], v[92:95]
	s_setprio 0
	s_setprio 1
	v_mfma_f32_16x16x32_bf16 v[136:139], v[176:179], v[194:197], 0
	v_mfma_f32_16x16x32_bf16 v[132:135], v[186:189], v[194:197], 0
	v_mfma_f32_16x16x32_bf16 v[120:123], v[176:179], v[202:205], 0
	v_mfma_f32_16x16x32_bf16 v[116:119], v[186:189], v[202:205], 0
	v_mfma_f32_16x16x32_bf16 v[104:107], v[176:179], v[210:213], 0
	v_mfma_f32_16x16x32_bf16 v[100:103], v[186:189], v[210:213], 0
	v_mfma_f32_16x16x32_bf16 v[88:91], v[176:179], v[218:221], 0
	v_mfma_f32_16x16x32_bf16 v[84:87], v[186:189], v[218:221], 0
	v_mfma_f32_16x16x32_bf16 v[136:139], v[180:183], v[198:201], v[136:139]
	v_mfma_f32_16x16x32_bf16 v[132:135], v[190:193], v[198:201], v[132:135]
	v_mfma_f32_16x16x32_bf16 v[120:123], v[180:183], v[206:209], v[120:123]
	v_mfma_f32_16x16x32_bf16 v[116:119], v[190:193], v[206:209], v[116:119]
	v_mfma_f32_16x16x32_bf16 v[104:107], v[180:183], v[214:217], v[104:107]
	v_mfma_f32_16x16x32_bf16 v[100:103], v[190:193], v[214:217], v[100:103]
	v_mfma_f32_16x16x32_bf16 v[88:91], v[180:183], v[222:225], v[88:91]
	v_mfma_f32_16x16x32_bf16 v[84:87], v[190:193], v[222:225], v[84:87]
	s_setprio 0
	s_barrier
	s_add_i32 s3, s3, s44
	v_lshl_add_u64 v[164:165], s[28:29], 0, v[2:3]
	s_mov_b32 m0, s3
	ds_read_b128 v[194:197], v171 offset:16384
	ds_read_b128 v[198:201], v171 offset:17408
	ds_read_b128 v[202:205], v171 offset:18432
	ds_read_b128 v[206:209], v171 offset:19456
	ds_read_b128 v[210:213], v171 offset:20480
	ds_read_b128 v[214:217], v171 offset:21504
	ds_read_b128 v[218:221], v171 offset:22528
	ds_read_b128 v[222:225], v171 offset:23552
	global_load_lds_dwordx4 v[164:165], off
	s_add_i32 m0, s3, 0x2000
	s_add_u32 s42, s28, 0x80000
	v_lshl_add_u64 v[226:227], s[28:29], 0, v[150:151]
	s_addc_u32 s43, s29, 0
	s_add_i32 s3, s51, s44
	global_load_lds_dwordx4 v[226:227], off
	v_lshl_add_u64 v[34:35], s[42:43], 0, v[2:3]
	s_mov_b32 m0, s3
	v_lshl_add_u64 v[228:229], s[30:31], 0, v[0:1]
	global_load_lds_dwordx4 v[34:35], off
	v_lshl_add_u64 v[34:35], s[42:43], 0, v[150:151]
	s_add_i32 m0, s3, 0x2000
	v_lshl_add_u64 v[230:231], s[30:31], 0, v[148:149]
	global_load_lds_dwordx4 v[34:35], off
	s_mov_b32 m0, s48
	s_nop 0
	global_load_lds_dwordx4 v[228:229], off
	s_mov_b32 m0, s49
	s_nop 0
	global_load_lds_dwordx4 v[230:231], off
	s_waitcnt vmcnt(8)
	s_waitcnt lgkmcnt(0)
	s_setprio 1
	s_barrier
; #define PG8_STAGE(bufoff, gbase, voff) do { _Pragma("unroll") for (int _i = 0; _i < 2; ++_i) \
;         __builtin_amdgcn_global_load_lds((const unsigned*)((const char*)(gbase) + (voff)[_i]), (PG8_LAS unsigned*)(lds + (bufoff) + ldsw + _i * 8192), 16, 0, 0); } while (0)
; #define PG8_LDA(dst, b, h) do { _Pragma("unroll") for (int m = 0; m < 4; ++m) _Pragma("unroll") for (int k = 0; k < 2; ++k) dst[m][k] = *(const PG8_LAS bf16x8*)(lds + PG8_SA(b, h) + aoff + m * 2048 + k * 1024); } while (0)
; #define PG8_LDB(dst, b, h) do { _Pragma("unroll") for (int n = 0; n < 2; ++n) _Pragma("unroll") for (int k = 0; k < 2; ++k) dst[n][k] = *(const PG8_LAS bf16x8*)(lds + PG8_SB(b, h) + boff + n * 2048 + k * 1024); } while (0)
; #define PG8_MMA(ai, bj, At, Bt) do { __builtin_amdgcn_s_setprio(1); _Pragma("unroll") for (int m = 0; m < 4; ++m) _Pragma("unroll") for (int n = 0; n < 2; ++n) _Pragma("unroll") for (int k = 0; k < 2; ++k) \
;         acc[ai][bj][m][n] = __builtin_amdgcn_mfma_f32_16x16x32_bf16(Bt[n][k], At[m][k], acc[ai][bj][m][n], 0, 0, 0); __builtin_amdgcn_s_setprio(0); } while (0)
; #define PG8_WAIT_V(n) asm volatile("s_waitcnt vmcnt(" #n ")" ::: "memory")
; #define PG8_WAIT_L(n) asm volatile("s_waitcnt lgkmcnt(" #n ")" ::: "memory")
; #define PG8_BAR __builtin_amdgcn_s_barrier()
; #define PG8_SCHED __builtin_amdgcn_sched_barrier(0)
; template <class Epi, class Sched, bool ALIGN_EPI = false, bool SP2 = false>
; __device__ __forceinline__ void gemm_phase(PG8_LAS unsigned char* lds, const Gemm g, const Sched& S, const Epi& E, const int tid) {
;     ...
;             PG8_WAIT_V(8); PG8_WAIT_L(0); PG8_BAR; PG8_MMA(0, 0, At, B0); PG8_MMA(0, 1, At, B1); PG8_BAR; PG8_SCHED;
;             PG8_LDA(At, 0, 1); PG8_STAGE(PG8_SB(0, 0), b2, voffB); PG8_STAGE(PG8_SB(0, 1), b2 + hstep, voffB); PG8_STAGE(PG8_SA(0, 0), a2, voffA);
;             PG8_WAIT_V(8); PG8_WAIT_L(0); PG8_BAR; PG8_MMA(1, 0, At, B0); PG8_MMA(1, 1, At, B1); PG8_BAR; PG8_SCHED;
;             PG8_LDB(B0, 1, 0); PG8_LDB(B1, 1, 1); PG8_SCHED; PG8_LDA(At, 1, 0); PG8_STAGE(PG8_SA(0, 1), a2 + hstep, voffA);
;             PG8_WAIT_V(8); PG8_WAIT_L(0); PG8_BAR; PG8_MMA(0, 0, At, B0); PG8_MMA(0, 1, At, B1); PG8_BAR; PG8_SCHED;
	v_mfma_f32_16x16x32_bf16 v[80:83], v[44:47], v[194:197], 0
	v_mfma_f32_16x16x32_bf16 v[76:79], v[160:163], v[194:197], 0
	v_mfma_f32_16x16x32_bf16 v[64:67], v[44:47], v[202:205], 0
	v_mfma_f32_16x16x32_bf16 v[60:63], v[160:163], v[202:205], 0
	v_mfma_f32_16x16x32_bf16 v[40:43], v[44:47], v[210:213], 0
	v_mfma_f32_16x16x32_bf16 v[34:37], v[160:163], v[210:213], 0
	v_mfma_f32_16x16x32_bf16 v[16:19], v[44:47], v[218:221], 0
	v_mfma_f32_16x16x32_bf16 v[12:15], v[160:163], v[218:221], 0
	v_mfma_f32_16x16x32_bf16 v[80:83], v[48:51], v[198:201], v[80:83]
	v_mfma_f32_16x16x32_bf16 v[76:79], v[172:175], v[198:201], v[76:79]
	v_mfma_f32_16x16x32_bf16 v[64:67], v[48:51], v[206:209], v[64:67]
	v_mfma_f32_16x16x32_bf16 v[60:63], v[172:175], v[206:209], v[60:63]
	v_mfma_f32_16x16x32_bf16 v[40:43], v[48:51], v[214:217], v[40:43]
	v_mfma_f32_16x16x32_bf16 v[34:37], v[172:175], v[214:217], v[34:37]
	v_mfma_f32_16x16x32_bf16 v[16:19], v[48:51], v[222:225], v[16:19]
	v_mfma_f32_16x16x32_bf16 v[12:15], v[172:175], v[222:225], v[12:15]
	s_setprio 0
	s_setprio 1
	v_mfma_f32_16x16x32_bf16 v[56:59], v[176:179], v[202:205], 0
	v_mfma_f32_16x16x32_bf16 v[52:55], v[186:189], v[202:205], 0
	v_mfma_f32_16x16x32_bf16 v[24:27], v[176:179], v[210:213], 0
	v_mfma_f32_16x16x32_bf16 v[20:23], v[186:189], v[210:213], 0
	v_mfma_f32_16x16x32_bf16 v[8:11], v[176:179], v[218:221], 0
	v_mfma_f32_16x16x32_bf16 v[4:7], v[186:189], v[218:221], 0
	v_mfma_f32_16x16x32_bf16 v[44:47], v[176:179], v[194:197], 0
	v_mfma_f32_16x16x32_bf16 v[48:51], v[186:189], v[194:197], 0
	v_mfma_f32_16x16x32_bf16 v[56:59], v[180:183], v[206:209], v[56:59]
	v_mfma_f32_16x16x32_bf16 v[52:55], v[190:193], v[206:209], v[52:55]
	v_mfma_f32_16x16x32_bf16 v[24:27], v[180:183], v[214:217], v[24:27]
	v_mfma_f32_16x16x32_bf16 v[20:23], v[190:193], v[214:217], v[20:23]
	v_mfma_f32_16x16x32_bf16 v[8:11], v[180:183], v[222:225], v[8:11]
	v_mfma_f32_16x16x32_bf16 v[4:7], v[190:193], v[222:225], v[4:7]
	v_mfma_f32_16x16x32_bf16 v[44:47], v[180:183], v[198:201], v[44:47]
	v_mfma_f32_16x16x32_bf16 v[48:51], v[190:193], v[198:201], v[48:51]
	s_setprio 0
	s_barrier
	s_add_i32 s3, 0, 0x18000
	v_add_u32_e32 v38, s3, v167
	s_add_i32 s42, 0, 0x1c000
	ds_read_b128 v[68:71], v38
	ds_read_b128 v[72:75], v38 offset:1024
	ds_read_b128 v[160:163], v38 offset:2048
	ds_read_b128 v[172:175], v38 offset:3072
	v_add_u32_e32 v38, s42, v167
	ds_read_b128 v[176:179], v38
	ds_read_b128 v[180:183], v38 offset:1024
	ds_read_b128 v[186:189], v38 offset:2048
	ds_read_b128 v[190:193], v38 offset:3072
	s_add_u32 s30, s30, 0x80000
	s_addc_u32 s31, s31, 0
	s_mov_b32 m0, s52
	v_lshl_add_u64 v[38:39], s[30:31], 0, v[0:1]
	ds_read_b128 v[194:197], v171 offset:32768
	ds_read_b128 v[198:201], v171 offset:33792
	ds_read_b128 v[202:205], v171 offset:34816
	ds_read_b128 v[206:209], v171 offset:35840
	ds_read_b128 v[210:213], v171 offset:36864
	ds_read_b128 v[214:217], v171 offset:37888
	ds_read_b128 v[218:221], v171 offset:38912
	ds_read_b128 v[222:225], v171 offset:39936
	global_load_lds_dwordx4 v[38:39], off
	v_lshl_add_u64 v[38:39], s[30:31], 0, v[148:149]
	s_mov_b32 m0, s53
	s_nop 0
	global_load_lds_dwordx4 v[38:39], off
	s_waitcnt vmcnt(8)
	s_waitcnt lgkmcnt(0)
	s_setprio 1
	s_barrier
	v_mfma_f32_16x16x32_bf16 v[144:147], v[68:71], v[194:197], v[144:147]
	v_mfma_f32_16x16x32_bf16 v[140:143], v[160:163], v[194:197], v[140:143]
	v_mfma_f32_16x16x32_bf16 v[128:131], v[68:71], v[202:205], v[128:131]
	v_mfma_f32_16x16x32_bf16 v[124:127], v[160:163], v[202:205], v[124:127]
	v_mfma_f32_16x16x32_bf16 v[112:115], v[68:71], v[210:213], v[112:115]
	v_mfma_f32_16x16x32_bf16 v[108:111], v[160:163], v[210:213], v[108:111]
	v_mfma_f32_16x16x32_bf16 v[96:99], v[68:71], v[218:221], v[96:99]
	v_mfma_f32_16x16x32_bf16 v[92:95], v[160:163], v[218:221], v[92:95]
	v_mfma_f32_16x16x32_bf16 v[144:147], v[72:75], v[198:201], v[144:147]
	v_mfma_f32_16x16x32_bf16 v[140:143], v[172:175], v[198:201], v[140:143]
	v_mfma_f32_16x16x32_bf16 v[128:131], v[72:75], v[206:209], v[128:131]
	v_mfma_f32_16x16x32_bf16 v[124:127], v[172:175], v[206:209], v[124:127]
	v_mfma_f32_16x16x32_bf16 v[112:115], v[72:75], v[214:217], v[112:115]
	v_mfma_f32_16x16x32_bf16 v[108:111], v[172:175], v[214:217], v[108:111]
	v_mfma_f32_16x16x32_bf16 v[96:99], v[72:75], v[222:225], v[96:99]
	v_mfma_f32_16x16x32_bf16 v[92:95], v[172:175], v[222:225], v[92:95]
	s_setprio 0
	s_setprio 1
	v_mfma_f32_16x16x32_bf16 v[136:139], v[176:179], v[194:197], v[136:139]
	v_mfma_f32_16x16x32_bf16 v[132:135], v[186:189], v[194:197], v[132:135]
	v_mfma_f32_16x16x32_bf16 v[120:123], v[176:179], v[202:205], v[120:123]
	v_mfma_f32_16x16x32_bf16 v[116:119], v[186:189], v[202:205], v[116:119]
	v_mfma_f32_16x16x32_bf16 v[104:107], v[176:179], v[210:213], v[104:107]
	v_mfma_f32_16x16x32_bf16 v[100:103], v[186:189], v[210:213], v[100:103]
	v_mfma_f32_16x16x32_bf16 v[88:91], v[176:179], v[218:221], v[88:91]
	v_mfma_f32_16x16x32_bf16 v[84:87], v[186:189], v[218:221], v[84:87]
	v_mfma_f32_16x16x32_bf16 v[136:139], v[180:183], v[198:201], v[136:139]
	v_mfma_f32_16x16x32_bf16 v[132:135], v[190:193], v[198:201], v[132:135]
	v_mfma_f32_16x16x32_bf16 v[120:123], v[180:183], v[206:209], v[120:123]
	v_mfma_f32_16x16x32_bf16 v[116:119], v[190:193], v[206:209], v[116:119]
	v_mfma_f32_16x16x32_bf16 v[104:107], v[180:183], v[214:217], v[104:107]
	v_mfma_f32_16x16x32_bf16 v[100:103], v[190:193], v[214:217], v[100:103]
	v_mfma_f32_16x16x32_bf16 v[88:91], v[180:183], v[222:225], v[88:91]
	v_mfma_f32_16x16x32_bf16 v[84:87], v[190:193], v[222:225], v[84:87]
	s_setprio 0
	s_barrier
; #define PG8_STAGE(bufoff, gbase, voff) do { _Pragma("unroll") for (int _i = 0; _i < 2; ++_i) \
;         __builtin_amdgcn_global_load_lds((const unsigned*)((const char*)(gbase) + (voff)[_i]), (PG8_LAS unsigned*)(lds + (bufoff) + ldsw + _i * 8192), 16, 0, 0); } while (0)
; #define PG8_LDA(dst, b, h) do { _Pragma("unroll") for (int m = 0; m < 4; ++m) _Pragma("unroll") for (int k = 0; k < 2; ++k) dst[m][k] = *(const PG8_LAS bf16x8*)(lds + PG8_SA(b, h) + aoff + m * 2048 + k * 1024); } while (0)
; #define PG8_LDB(dst, b, h) do { _Pragma("unroll") for (int n = 0; n < 2; ++n) _Pragma("unroll") for (int k = 0; k < 2; ++k) dst[n][k] = *(const PG8_LAS bf16x8*)(lds + PG8_SB(b, h) + boff + n * 2048 + k * 1024); } while (0)
; #define PG8_MMA(ai, bj, At, Bt) do { __builtin_amdgcn_s_setprio(1); _Pragma("unroll") for (int m = 0; m < 4; ++m) _Pragma("unroll") for (int n = 0; n < 2; ++n) _Pragma("unroll") for (int k = 0; k < 2; ++k) \
;         acc[ai][bj][m][n] = __builtin_amdgcn_mfma_f32_16x16x32_bf16(Bt[n][k], At[m][k], acc[ai][bj][m][n], 0, 0, 0); __builtin_amdgcn_s_setprio(0); } while (0)
; #define PG8_WAIT_V(n) asm volatile("s_waitcnt vmcnt(" #n ")" ::: "memory")
; #define PG8_WAIT_L(n) asm volatile("s_waitcnt lgkmcnt(" #n ")" ::: "memory")
; #define PG8_BAR __builtin_amdgcn_s_barrier()
; #define PG8_SCHED __builtin_amdgcn_sched_barrier(0)
; template <class Epi, class Sched, bool ALIGN_EPI = false, bool SP2 = false>
; __device__ __forceinline__ void gemm_phase(PG8_LAS unsigned char* lds, const Gemm g, const Sched& S, const Epi& E, const int tid) {
;     ...
;         for (int t = 0; t < nt; t += 2) {
;             const bool last = (t == nt - 2);
;     ...
;             PG8_LDB(B0, 1, 0); PG8_LDB(B1, 1, 1); PG8_SCHED; PG8_LDA(At, 1, 0); PG8_STAGE(PG8_SA(0, 1), a2 + hstep, voffA);
;             PG8_WAIT_V(8); PG8_WAIT_L(0); PG8_BAR; PG8_MMA(0, 0, At, B0); PG8_MMA(0, 1, At, B1); PG8_BAR; PG8_SCHED;
;             PG8_LDA(At, 1, 1); PG8_STAGE(PG8_SB(1, 0), b3, voffB); PG8_STAGE(PG8_SB(1, 1), b3 + hstep, voffB); PG8_STAGE(PG8_SA(1, 0), a3, voffA);
;             PG8_WAIT_V(8); PG8_WAIT_L(0); PG8_BAR; PG8_MMA(1, 0, At, B0); PG8_MMA(1, 1, At, B1); PG8_BAR; PG8_SCHED;
	s_add_i32 s3, s3, s44
	v_lshl_add_u64 v[38:39], v[164:165], 0, s[46:47]
	s_mov_b32 m0, s3
	ds_read_b128 v[194:197], v171 offset:49152
	ds_read_b128 v[198:201], v171 offset:50176
	ds_read_b128 v[202:205], v171 offset:51200
	ds_read_b128 v[206:209], v171 offset:52224
	ds_read_b128 v[210:213], v171 offset:53248
	ds_read_b128 v[214:217], v171 offset:54272
	ds_read_b128 v[218:221], v171 offset:55296
	ds_read_b128 v[222:225], v171 offset:56320
	global_load_lds_dwordx4 v[38:39], off
	s_add_i32 m0, s3, 0x2000
	s_add_u32 s28, s28, 0x80080
	v_lshl_add_u64 v[38:39], v[226:227], 0, s[46:47]
	s_addc_u32 s29, s29, 0
	s_add_i32 s3, s42, s44
	global_load_lds_dwordx4 v[38:39], off
	v_lshl_add_u64 v[38:39], s[28:29], 0, v[2:3]
	s_mov_b32 m0, s3
	s_nop 0
	global_load_lds_dwordx4 v[38:39], off
	v_lshl_add_u64 v[38:39], s[28:29], 0, v[150:151]
	s_add_i32 m0, s3, 0x2000
	s_nop 0
	global_load_lds_dwordx4 v[38:39], off
	v_lshl_add_u64 v[38:39], v[228:229], 0, s[46:47]
	s_mov_b32 m0, s5
	s_nop 0
	global_load_lds_dwordx4 v[38:39], off
	v_lshl_add_u64 v[38:39], v[230:231], 0, s[46:47]
	s_mov_b32 m0, s54
	s_nop 0
	global_load_lds_dwordx4 v[38:39], off
	s_waitcnt vmcnt(8)
	s_waitcnt lgkmcnt(0)
	s_setprio 1
	s_barrier
	v_mfma_f32_16x16x32_bf16 v[80:83], v[68:71], v[194:197], v[80:83]
	v_mfma_f32_16x16x32_bf16 v[76:79], v[160:163], v[194:197], v[76:79]
	v_mfma_f32_16x16x32_bf16 v[64:67], v[68:71], v[202:205], v[64:67]
	v_mfma_f32_16x16x32_bf16 v[60:63], v[160:163], v[202:205], v[60:63]
	v_mfma_f32_16x16x32_bf16 v[38:41], v[68:71], v[210:213], v[40:43]
	v_mfma_f32_16x16x32_bf16 v[34:37], v[160:163], v[210:213], v[34:37]
	v_mfma_f32_16x16x32_bf16 v[16:19], v[68:71], v[218:221], v[16:19]
	v_mfma_f32_16x16x32_bf16 v[12:15], v[160:163], v[218:221], v[12:15]
	v_mfma_f32_16x16x32_bf16 v[80:83], v[72:75], v[198:201], v[80:83]
	v_mfma_f32_16x16x32_bf16 v[76:79], v[172:175], v[198:201], v[76:79]
	v_mfma_f32_16x16x32_bf16 v[64:67], v[72:75], v[206:209], v[64:67]
	v_mfma_f32_16x16x32_bf16 v[60:63], v[172:175], v[206:209], v[60:63]
	v_mfma_f32_16x16x32_bf16 v[40:43], v[72:75], v[214:217], v[38:41]
	v_mfma_f32_16x16x32_bf16 v[36:39], v[172:175], v[214:217], v[34:37]
	v_mfma_f32_16x16x32_bf16 v[16:19], v[72:75], v[222:225], v[16:19]
	v_mfma_f32_16x16x32_bf16 v[12:15], v[172:175], v[222:225], v[12:15]
	s_setprio 0
	s_setprio 1
	v_mfma_f32_16x16x32_bf16 v[44:47], v[176:179], v[194:197], v[44:47]
	v_mfma_f32_16x16x32_bf16 v[72:75], v[180:183], v[198:201], v[44:47]
	v_mfma_f32_16x16x32_bf16 v[44:47], v[186:189], v[194:197], v[48:51]
	v_mfma_f32_16x16x32_bf16 v[68:71], v[190:193], v[198:201], v[44:47]
	v_mfma_f32_16x16x32_bf16 v[44:47], v[176:179], v[202:205], v[56:59]
	v_mfma_f32_16x16x32_bf16 v[56:59], v[180:183], v[206:209], v[44:47]
	v_mfma_f32_16x16x32_bf16 v[44:47], v[186:189], v[202:205], v[52:55]
	v_mfma_f32_16x16x32_bf16 v[24:27], v[176:179], v[210:213], v[24:27]
	v_mfma_f32_16x16x32_bf16 v[20:23], v[186:189], v[210:213], v[20:23]
	v_mfma_f32_16x16x32_bf16 v[8:11], v[176:179], v[218:221], v[8:11]
	v_mfma_f32_16x16x32_bf16 v[4:7], v[186:189], v[218:221], v[4:7]
	v_mfma_f32_16x16x32_bf16 v[52:55], v[190:193], v[206:209], v[44:47]
	v_mfma_f32_16x16x32_bf16 v[24:27], v[180:183], v[214:217], v[24:27]
	v_mfma_f32_16x16x32_bf16 v[20:23], v[190:193], v[214:217], v[20:23]
	v_mfma_f32_16x16x32_bf16 v[8:11], v[180:183], v[222:225], v[8:11]
	v_mfma_f32_16x16x32_bf16 v[4:7], v[190:193], v[222:225], v[4:7]
	s_setprio 0
	s_barrier
	s_add_i32 s50, s50, 2
	s_add_u32 s26, s26, 0x100
	s_addc_u32 s27, s27, 0
	s_add_u32 s23, s23, 0x100
	s_addc_u32 s25, s25, 0
	s_cmp_gt_u32 s50, 29
	s_cbranch_scc1 .LBB0_159
	s_branch .LBB0_157
